# odd attention softmax: packed f32 fma for exp argument in place, exp in place, packed row sums right after exp
# speedup vs baseline: 1.0159x; 1.0027x over previous
.LBB0_430:
	ds_read_b128 v[158:161], v153 offset:4608
	ds_read_b128 v[162:165], v153 offset:4672
	ds_read_b128 v[112:115], v153
	ds_read_b128 v[116:119], v153 offset:64
	s_waitcnt lgkmcnt(3)
	v_mfma_f32_16x16x32_bf16 v[158:161], v[158:161], v[0:3], 0
	ds_read_b128 v[168:171], v153 offset:9280
	ds_read_b128 v[174:177], v153 offset:13888
	s_waitcnt lgkmcnt(4)
	v_mfma_f32_16x16x32_bf16 v[160:163], v[162:165], v[4:7], v[158:161]
	ds_read_b128 v[164:167], v153 offset:9216
	s_waitcnt lgkmcnt(0)
	v_mfma_f32_16x16x32_bf16 v[164:167], v[164:167], v[0:3], 0
	s_nop 4
	s_nop 0
	v_mfma_f32_16x16x32_bf16 v[166:169], v[168:171], v[4:7], v[164:167]
	ds_read_b128 v[170:173], v153 offset:13824
	v_mfma_f32_16x16x32_bf16 v[112:115], v[112:115], v[0:3], 0
	s_nop 0
	s_nop 0
	s_nop 3
	s_nop 0
	s_nop 0
	v_mfma_f32_16x16x32_bf16 v[114:117], v[116:119], v[4:7], v[112:115]
	s_nop 0
	s_waitcnt lgkmcnt(0)
	v_mfma_f32_16x16x32_bf16 v[170:173], v[170:173], v[0:3], 0
	v_mfma_f32_16x16x32_bf16 v[170:173], v[174:177], v[4:7], v[170:173]
	s_nop 7
	s_nop 1
	v_max3_f32 v194, v114, s30, v115
	v_max3_f32 v194, v194, v116, v117
	v_max3_f32 v194, v194, v160, v161
	v_max3_f32 v194, v194, v162, v163
	v_max3_f32 v194, v194, v166, v167
	v_max3_f32 v194, v194, v168, v169
	v_max3_f32 v194, v194, v170, v171
	v_max3_f32 v194, v194, v172, v173
	v_mov_b32_e32 v195, v194
	s_nop 1
	v_permlane16_swap_b32_e32 v194, v195
	v_max_f32_e32 v195, v195, v195
	v_max_f32_e32 v194, v194, v194
	v_max_f32_e32 v194, v194, v195
	v_mov_b32_e32 v195, v194
	s_nop 1
	v_permlane32_swap_b32_e32 v194, v195
	v_max_f32_e32 v194, v194, v195
	v_mul_f32_e32 v194, 0x3e38aa3b, v194
	v_max_f32_e32 v194, v155, v194
	v_pk_fma_f32 v[114:115], v[114:115], s[32:33], v[194:195] op_sel_hi:[1,0,0] neg_lo:[0,0,1] neg_hi:[0,0,1]
	v_pk_fma_f32 v[116:117], v[116:117], s[32:33], v[194:195] op_sel_hi:[1,0,0] neg_lo:[0,0,1] neg_hi:[0,0,1]
	v_pk_fma_f32 v[160:161], v[160:161], s[32:33], v[194:195] op_sel_hi:[1,0,0] neg_lo:[0,0,1] neg_hi:[0,0,1]
	v_pk_fma_f32 v[162:163], v[162:163], s[32:33], v[194:195] op_sel_hi:[1,0,0] neg_lo:[0,0,1] neg_hi:[0,0,1]
	v_pk_fma_f32 v[166:167], v[166:167], s[32:33], v[194:195] op_sel_hi:[1,0,0] neg_lo:[0,0,1] neg_hi:[0,0,1]
	v_pk_fma_f32 v[168:169], v[168:169], s[32:33], v[194:195] op_sel_hi:[1,0,0] neg_lo:[0,0,1] neg_hi:[0,0,1]
	v_pk_fma_f32 v[170:171], v[170:171], s[32:33], v[194:195] op_sel_hi:[1,0,0] neg_lo:[0,0,1] neg_hi:[0,0,1]
	v_pk_fma_f32 v[172:173], v[172:173], s[32:33], v[194:195] op_sel_hi:[1,0,0] neg_lo:[0,0,1] neg_hi:[0,0,1]
	v_cmp_gt_f32_e32 vcc, v194, v155
	s_cbranch_vccz .LBB0_432
	v_sub_f32_e32 v155, v155, v194
	v_exp_f32_e32 v215, v155
	v_mov_b32_e32 v155, v194
	v_mul_f32_e32 v131, v131, v215
	v_pk_mul_f32 v[98:99], v[98:99], v[214:215] op_sel:[0,1] op_sel_hi:[1,1]
	v_pk_mul_f32 v[96:97], v[96:97], v[214:215] op_sel:[0,1] op_sel_hi:[1,1]
	v_pk_mul_f32 v[102:103], v[102:103], v[214:215] op_sel:[0,1] op_sel_hi:[1,1]
	v_pk_mul_f32 v[100:101], v[100:101], v[214:215] op_sel:[0,1] op_sel_hi:[1,1]
	v_pk_mul_f32 v[70:71], v[70:71], v[214:215] op_sel:[0,1] op_sel_hi:[1,1]
	v_pk_mul_f32 v[68:69], v[68:69], v[214:215] op_sel:[0,1] op_sel_hi:[1,1]
	v_pk_mul_f32 v[54:55], v[54:55], v[214:215] op_sel:[0,1] op_sel_hi:[1,1]
	v_pk_mul_f32 v[52:53], v[52:53], v[214:215] op_sel:[0,1] op_sel_hi:[1,1]
	v_pk_mul_f32 v[82:83], v[82:83], v[214:215] op_sel:[0,1] op_sel_hi:[1,1]
	v_pk_mul_f32 v[80:81], v[80:81], v[214:215] op_sel:[0,1] op_sel_hi:[1,1]
	v_pk_mul_f32 v[86:87], v[86:87], v[214:215] op_sel:[0,1] op_sel_hi:[1,1]
	v_pk_mul_f32 v[84:85], v[84:85], v[214:215] op_sel:[0,1] op_sel_hi:[1,1]
	v_pk_mul_f32 v[78:79], v[78:79], v[214:215] op_sel:[0,1] op_sel_hi:[1,1]
	v_pk_mul_f32 v[76:77], v[76:77], v[214:215] op_sel:[0,1] op_sel_hi:[1,1]
	v_pk_mul_f32 v[110:111], v[110:111], v[214:215] op_sel:[0,1] op_sel_hi:[1,1]
	v_pk_mul_f32 v[108:109], v[108:109], v[214:215] op_sel:[0,1] op_sel_hi:[1,1]
.LBB0_432:
	v_exp_f32_e32 v114, v114
	v_exp_f32_e32 v115, v115
	v_exp_f32_e32 v116, v116
	v_exp_f32_e32 v117, v117
	v_exp_f32_e32 v160, v160
	v_exp_f32_e32 v161, v161
	v_exp_f32_e32 v162, v162
	v_exp_f32_e32 v163, v163
	v_exp_f32_e32 v166, v166
	v_exp_f32_e32 v167, v167
	v_exp_f32_e32 v168, v168
	v_exp_f32_e32 v169, v169
	v_exp_f32_e32 v170, v170
	v_exp_f32_e32 v171, v171
	v_exp_f32_e32 v172, v172
	v_exp_f32_e32 v173, v173
	s_nop 0
	v_cvt_pk_bf16_f32 v216, v114, v115
	v_cvt_pk_bf16_f32 v218, v160, v161
	v_cvt_pk_bf16_f32 v220, v166, v167
	v_cvt_pk_bf16_f32 v222, v170, v171
	v_pk_add_f32 v[114:115], v[114:115], v[116:117]
	v_pk_add_f32 v[160:161], v[160:161], v[162:163]
	v_pk_add_f32 v[166:167], v[166:167], v[168:169]
	v_pk_add_f32 v[170:171], v[170:171], v[172:173]
	v_pk_add_f32 v[114:115], v[114:115], v[160:161]
	v_pk_add_f32 v[170:171], v[170:171], v[166:167]
	v_cvt_pk_bf16_f32 v217, v116, v117
	v_pk_add_f32 v[170:171], v[170:171], v[114:115]
	v_cvt_pk_bf16_f32 v219, v162, v163
	v_add_f32_e32 v170, v170, v171
	v_cvt_pk_bf16_f32 v221, v168, v169
	v_add_f32_e32 v131, v170, v131
	v_cvt_pk_bf16_f32 v223, v172, v173
	ds_read_b128 v[112:115], v153 offset:128
	ds_read_b128 v[116:119], v153 offset:192
	s_waitcnt lgkmcnt(1)
	v_mfma_f32_16x16x32_bf16 v[112:115], v[112:115], v[8:11], 0
	ds_read_b128 v[158:161], v153 offset:4736
	ds_read_b128 v[162:165], v153 offset:9344
	ds_read_b128 v[182:185], v153 offset:13952
	s_waitcnt lgkmcnt(3)
	v_mfma_f32_16x16x32_bf16 v[112:115], v[116:119], v[12:15], v[112:115]
	ds_read_b128 v[116:119], v153 offset:4800
	s_waitcnt lgkmcnt(3)
	v_mfma_f32_16x16x32_bf16 v[158:161], v[158:161], v[8:11], 0
	s_waitcnt lgkmcnt(0)
	v_mfma_f32_16x16x32_bf16 v[116:119], v[116:119], v[12:15], v[158:161]
	s_nop 5
	ds_read_b128 v[158:161], v153 offset:9408
	v_mfma_f32_16x16x32_bf16 v[162:165], v[162:165], v[8:11], 0
	s_waitcnt lgkmcnt(0)
	v_mfma_f32_16x16x32_bf16 v[186:189], v[158:161], v[12:15], v[162:165]
	ds_read_b128 v[158:161], v153 offset:14016
	s_nop 6
	s_nop 0
	v_mfma_f32_16x16x32_bf16 v[162:165], v[182:185], v[8:11], 0
	s_waitcnt lgkmcnt(0)
	v_mfma_f32_16x16x32_bf16 v[182:185], v[158:161], v[12:15], v[162:165]
	s_nop 7
	s_nop 1
	v_max3_f32 v194, v112, s30, v113
	v_max3_f32 v194, v194, v114, v115
	v_max3_f32 v194, v194, v116, v117
	v_max3_f32 v194, v194, v118, v119
	v_max3_f32 v194, v194, v186, v187
	v_max3_f32 v194, v194, v188, v189
	v_max3_f32 v194, v194, v182, v183
	v_max3_f32 v194, v194, v184, v185
	v_mov_b32_e32 v195, v194
	s_nop 1
	v_permlane16_swap_b32_e32 v194, v195
	v_max_f32_e32 v195, v195, v195
	v_max_f32_e32 v194, v194, v194
	v_max_f32_e32 v194, v194, v195
	v_mov_b32_e32 v195, v194
	s_nop 1
	v_permlane32_swap_b32_e32 v194, v195
	v_max_f32_e32 v194, v194, v195
	v_mul_f32_e32 v194, 0x3e38aa3b, v194
	v_max_f32_e32 v194, v156, v194
	v_pk_fma_f32 v[112:113], v[112:113], s[32:33], v[194:195] op_sel_hi:[1,0,0] neg_lo:[0,0,1] neg_hi:[0,0,1]
	v_pk_fma_f32 v[114:115], v[114:115], s[32:33], v[194:195] op_sel_hi:[1,0,0] neg_lo:[0,0,1] neg_hi:[0,0,1]
	v_pk_fma_f32 v[116:117], v[116:117], s[32:33], v[194:195] op_sel_hi:[1,0,0] neg_lo:[0,0,1] neg_hi:[0,0,1]
	v_pk_fma_f32 v[118:119], v[118:119], s[32:33], v[194:195] op_sel_hi:[1,0,0] neg_lo:[0,0,1] neg_hi:[0,0,1]
	v_pk_fma_f32 v[186:187], v[186:187], s[32:33], v[194:195] op_sel_hi:[1,0,0] neg_lo:[0,0,1] neg_hi:[0,0,1]
	v_pk_fma_f32 v[188:189], v[188:189], s[32:33], v[194:195] op_sel_hi:[1,0,0] neg_lo:[0,0,1] neg_hi:[0,0,1]
	v_pk_fma_f32 v[182:183], v[182:183], s[32:33], v[194:195] op_sel_hi:[1,0,0] neg_lo:[0,0,1] neg_hi:[0,0,1]
	v_pk_fma_f32 v[184:185], v[184:185], s[32:33], v[194:195] op_sel_hi:[1,0,0] neg_lo:[0,0,1] neg_hi:[0,0,1]
	v_cmp_gt_f32_e32 vcc, v194, v156
	s_cbranch_vccz .LBB0_434
	v_sub_f32_e32 v156, v156, v194
	v_exp_f32_e32 v156, v156
	s_nop 0
	v_mul_f32_e32 v121, v121, v156
	v_pk_mul_f32 v[94:95], v[94:95], v[156:157] op_sel_hi:[1,0]
	v_pk_mul_f32 v[92:93], v[92:93], v[156:157] op_sel_hi:[1,0]
	v_pk_mul_f32 v[90:91], v[90:91], v[156:157] op_sel_hi:[1,0]
	v_pk_mul_f32 v[88:89], v[88:89], v[156:157] op_sel_hi:[1,0]
	v_pk_mul_f32 v[58:59], v[58:59], v[156:157] op_sel_hi:[1,0]
	v_pk_mul_f32 v[56:57], v[56:57], v[156:157] op_sel_hi:[1,0]
	v_pk_mul_f32 v[50:51], v[50:51], v[156:157] op_sel_hi:[1,0]
	v_pk_mul_f32 v[48:49], v[48:49], v[156:157] op_sel_hi:[1,0]
	v_pk_mul_f32 v[66:67], v[66:67], v[156:157] op_sel_hi:[1,0]
	v_pk_mul_f32 v[64:65], v[64:65], v[156:157] op_sel_hi:[1,0]
	v_pk_mul_f32 v[74:75], v[74:75], v[156:157] op_sel_hi:[1,0]
	v_pk_mul_f32 v[72:73], v[72:73], v[156:157] op_sel_hi:[1,0]
	v_pk_mul_f32 v[62:63], v[62:63], v[156:157] op_sel_hi:[1,0]
	v_pk_mul_f32 v[60:61], v[60:61], v[156:157] op_sel_hi:[1,0]
	v_pk_mul_f32 v[106:107], v[106:107], v[156:157] op_sel_hi:[1,0]
	v_pk_mul_f32 v[104:105], v[104:105], v[156:157] op_sel_hi:[1,0]
	v_mov_b32_e32 v156, v194
.LBB0_434:
	v_exp_f32_e32 v112, v112
	v_exp_f32_e32 v113, v113
	v_exp_f32_e32 v114, v114
	v_exp_f32_e32 v115, v115
	v_exp_f32_e32 v116, v116
	v_exp_f32_e32 v117, v117
	v_exp_f32_e32 v118, v118
	v_exp_f32_e32 v119, v119
	v_exp_f32_e32 v186, v186
	v_exp_f32_e32 v187, v187
	v_exp_f32_e32 v188, v188
	v_exp_f32_e32 v189, v189
	v_exp_f32_e32 v182, v182
	v_exp_f32_e32 v183, v183
	v_exp_f32_e32 v184, v184
	v_exp_f32_e32 v185, v185
	s_nop 0
	v_cvt_pk_bf16_f32 v224, v112, v113
	v_cvt_pk_bf16_f32 v226, v116, v117
	v_cvt_pk_bf16_f32 v230, v186, v187
	v_cvt_pk_bf16_f32 v232, v182, v183
	v_pk_add_f32 v[112:113], v[112:113], v[114:115]
	v_pk_add_f32 v[116:117], v[116:117], v[118:119]
	v_pk_add_f32 v[186:187], v[186:187], v[188:189]
	v_pk_add_f32 v[182:183], v[182:183], v[184:185]
	v_pk_add_f32 v[112:113], v[112:113], v[116:117]
	v_pk_add_f32 v[182:183], v[182:183], v[186:187]
	v_cvt_pk_bf16_f32 v225, v114, v115
	v_pk_add_f32 v[182:183], v[182:183], v[112:113]
	v_cvt_pk_bf16_f32 v227, v118, v119
	v_add_f32_e32 v182, v182, v183
	v_cvt_pk_bf16_f32 v231, v188, v189
	v_add_f32_e32 v121, v182, v121
	v_cvt_pk_bf16_f32 v233, v184, v185
	s_cmp_lg_u32 s26, s27
	v_bfe_u32 v214, v228, 4, 2
	v_mul_u32_u24_e32 v214, 0x440, v214
	v_sub_u32_e32 v214, v152, v214
	ds_read_b64_tr_b16 v[198:199], v214 offset:18432
	ds_read_b64_tr_b16 v[200:201], v214 offset:22784
	ds_read_b64_tr_b16 v[202:203], v214 offset:18464
	ds_read_b64_tr_b16 v[204:205], v214 offset:22816
	ds_read_b64_tr_b16 v[206:207], v214 offset:18496
	ds_read_b64_tr_b16 v[208:209], v214 offset:22848
	ds_read_b64_tr_b16 v[210:211], v214 offset:18528
	ds_read_b64_tr_b16 v[212:213], v214 offset:22880
	s_waitcnt lgkmcnt(6)
	v_mfma_f32_16x16x32_bf16 v[96:99], v[198:201], v[216:219], v[96:99]
	v_mfma_f32_16x16x32_bf16 v[92:95], v[198:201], v[224:227], v[92:95]
	ds_read_b64_tr_b16 v[198:199], v214 offset:18560
	ds_read_b64_tr_b16 v[200:201], v214 offset:22912
	s_waitcnt lgkmcnt(6)
	v_mfma_f32_16x16x32_bf16 v[100:103], v[202:205], v[216:219], v[100:103]
	v_mfma_f32_16x16x32_bf16 v[88:91], v[202:205], v[224:227], v[88:91]
	ds_read_b64_tr_b16 v[202:203], v214 offset:18592
	ds_read_b64_tr_b16 v[204:205], v214 offset:22944
	s_waitcnt lgkmcnt(6)
	v_mfma_f32_16x16x32_bf16 v[68:71], v[206:209], v[216:219], v[68:71]
	v_mfma_f32_16x16x32_bf16 v[56:59], v[206:209], v[224:227], v[56:59]
	ds_read_b64_tr_b16 v[206:207], v214 offset:18624
	ds_read_b64_tr_b16 v[208:209], v214 offset:22976
	s_waitcnt lgkmcnt(6)
	v_mfma_f32_16x16x32_bf16 v[52:55], v[210:213], v[216:219], v[52:55]
	v_mfma_f32_16x16x32_bf16 v[48:51], v[210:213], v[224:227], v[48:51]
	ds_read_b64_tr_b16 v[210:211], v214 offset:18656
	ds_read_b64_tr_b16 v[212:213], v214 offset:23008
	s_waitcnt lgkmcnt(6)
	v_mfma_f32_16x16x32_bf16 v[80:83], v[198:201], v[216:219], v[80:83]
	v_mfma_f32_16x16x32_bf16 v[64:67], v[198:201], v[224:227], v[64:67]
	ds_read_b64_tr_b16 v[198:199], v214 offset:27136
	ds_read_b64_tr_b16 v[200:201], v214 offset:31488
	s_waitcnt lgkmcnt(6)
	v_mfma_f32_16x16x32_bf16 v[84:87], v[202:205], v[216:219], v[84:87]
	v_mfma_f32_16x16x32_bf16 v[72:75], v[202:205], v[224:227], v[72:75]
	ds_read_b64_tr_b16 v[202:203], v214 offset:27168
	ds_read_b64_tr_b16 v[204:205], v214 offset:31520
	s_waitcnt lgkmcnt(6)
	v_mfma_f32_16x16x32_bf16 v[76:79], v[206:209], v[216:219], v[76:79]
	v_mfma_f32_16x16x32_bf16 v[60:63], v[206:209], v[224:227], v[60:63]
	ds_read_b64_tr_b16 v[206:207], v214 offset:27200
	ds_read_b64_tr_b16 v[208:209], v214 offset:31552
	s_waitcnt lgkmcnt(6)
	v_mfma_f32_16x16x32_bf16 v[108:111], v[210:213], v[216:219], v[108:111]
	v_mfma_f32_16x16x32_bf16 v[104:107], v[210:213], v[224:227], v[104:107]
	ds_read_b64_tr_b16 v[210:211], v214 offset:27232
	ds_read_b64_tr_b16 v[212:213], v214 offset:31584
	s_waitcnt lgkmcnt(6)
	v_mfma_f32_16x16x32_bf16 v[96:99], v[198:201], v[220:223], v[96:99]
	v_mfma_f32_16x16x32_bf16 v[92:95], v[198:201], v[230:233], v[92:95]
	ds_read_b64_tr_b16 v[198:199], v214 offset:27264
	ds_read_b64_tr_b16 v[200:201], v214 offset:31616
	s_waitcnt lgkmcnt(6)
	v_mfma_f32_16x16x32_bf16 v[100:103], v[202:205], v[220:223], v[100:103]
	v_mfma_f32_16x16x32_bf16 v[88:91], v[202:205], v[230:233], v[88:91]
	ds_read_b64_tr_b16 v[202:203], v214 offset:27296
	ds_read_b64_tr_b16 v[204:205], v214 offset:31648
	s_waitcnt lgkmcnt(6)
	v_mfma_f32_16x16x32_bf16 v[68:71], v[206:209], v[220:223], v[68:71]
	v_mfma_f32_16x16x32_bf16 v[56:59], v[206:209], v[230:233], v[56:59]
	ds_read_b64_tr_b16 v[206:207], v214 offset:27328
	ds_read_b64_tr_b16 v[208:209], v214 offset:31680
	s_waitcnt lgkmcnt(6)
	v_mfma_f32_16x16x32_bf16 v[52:55], v[210:213], v[220:223], v[52:55]
	v_mfma_f32_16x16x32_bf16 v[48:51], v[210:213], v[230:233], v[48:51]
	ds_read_b64_tr_b16 v[210:211], v214 offset:27360
	ds_read_b64_tr_b16 v[212:213], v214 offset:31712
	s_waitcnt lgkmcnt(6)
	v_mfma_f32_16x16x32_bf16 v[80:83], v[198:201], v[220:223], v[80:83]
	v_mfma_f32_16x16x32_bf16 v[64:67], v[198:201], v[230:233], v[64:67]
	s_waitcnt lgkmcnt(4)
	v_mfma_f32_16x16x32_bf16 v[84:87], v[202:205], v[220:223], v[84:87]
	v_mfma_f32_16x16x32_bf16 v[72:75], v[202:205], v[230:233], v[72:75]
	s_waitcnt lgkmcnt(2)
	v_mfma_f32_16x16x32_bf16 v[76:79], v[206:209], v[220:223], v[76:79]
	v_mfma_f32_16x16x32_bf16 v[60:63], v[206:209], v[230:233], v[60:63]
	s_waitcnt lgkmcnt(0)
	v_mfma_f32_16x16x32_bf16 v[108:111], v[210:213], v[220:223], v[108:111]
	v_mfma_f32_16x16x32_bf16 v[104:107], v[210:213], v[230:233], v[104:107]
	s_cbranch_scc0 .LBB0_419
	s_mov_b32 s28, s27
	s_branch .LBB0_426
